# S5 tile loop: ssq reduction for the next tile placed in the latency shadow of the Zt LDS read (before its lgkmcnt wait)
# speedup vs baseline: 1.0093x; 1.0093x over previous
.LBB0_324:
	v_lshlrev_b32_e32 v6, 16, v0
	v_and_b32_e32 v7, 0xffff0000, v0
	v_lshlrev_b32_e32 v0, 16, v1
	v_and_b32_e32 v1, 0xffff0000, v1
	s_waitcnt vmcnt(6)
	v_pk_fma_f32 v[116:117], v[4:5], v[0:1], v[70:71] op_sel_hi:[0,1,1]
	v_lshlrev_b32_e32 v0, 16, v2
	v_and_b32_e32 v1, 0xffff0000, v2
	v_pk_fma_f32 v[118:119], v[4:5], v[0:1], v[64:65] op_sel_hi:[0,1,1]
	v_lshlrev_b32_e32 v0, 16, v3
	v_and_b32_e32 v1, 0xffff0000, v3
	v_pk_fma_f32 v[114:115], v[4:5], v[6:7], v[68:69] op_sel_hi:[0,1,1]
	v_pk_fma_f32 v[120:121], v[4:5], v[0:1], v[66:67] op_sel_hi:[0,1,1]
	v_cvt_pk_bf16_f32 v122, v114, v115
	v_cvt_pk_bf16_f32 v123, v116, v117
	v_cvt_pk_bf16_f32 v124, v118, v119
	v_cvt_pk_bf16_f32 v125, v120, v121
	s_mov_b64 s[22:23], 0x1000
	v_lshl_add_u64 v[94:95], v[94:95], 0, s[22:23]
	v_mfma_f32_32x32x16_bf16 v[16:31], v[122:125], v[32:35], 0
	v_mfma_f32_32x32x16_bf16 v[0:15], v[122:125], v[36:39], 0
	ds_write_b128 v102, v[114:117] offset:27136
	ds_write_b128 v102, v[118:121] offset:27152
	s_nop 8
	ds_write_b128 v106, v[16:19]
	ds_write_b128 v106, v[20:23] offset:32
	ds_write_b128 v106, v[24:27] offset:64
	ds_write_b128 v106, v[28:31] offset:96
	ds_write_b128 v106, v[0:3] offset:4608
	v_mfma_f32_32x32x16_bf16 v[16:31], v[122:125], v[40:43], 0
	ds_write_b128 v106, v[4:7] offset:4640
	ds_write_b128 v106, v[8:11] offset:4672
	ds_write_b128 v106, v[12:15] offset:4704
	s_nop 8
	ds_write_b128 v106, v[16:19] offset:9216
	ds_write_b128 v106, v[20:23] offset:9248
	ds_write_b128 v106, v[24:27] offset:9280
	ds_write_b128 v106, v[28:31] offset:9312
	v_mfma_f32_32x32x16_bf16 v[0:15], v[122:125], v[44:47], 0
	s_nop 11
	ds_write_b128 v106, v[0:3] offset:13824
	ds_write_b128 v106, v[4:7] offset:13856
	ds_write_b128 v106, v[8:11] offset:13888
	ds_write_b128 v106, v[12:15] offset:13920
	ds_read_b128 v[4:7], v107 offset:9216
	ds_read_b128 v[114:117], v107 offset:9232
	ds_read_b128 v[12:15], v107
	ds_read_b128 v[118:121], v107 offset:16
	ds_read_b128 v[122:125], v107 offset:32
	ds_read_b128 v[126:129], v107 offset:48
	ds_read_b128 v[130:133], v107 offset:9248
	ds_read_b128 v[134:137], v107 offset:9264
	ds_read_b128 v[28:31], v107 offset:64
	ds_read_b128 v[20:23], v107 offset:80
	ds_read_b128 v[24:27], v107 offset:9280
	ds_read_b128 v[16:19], v107 offset:9296
	ds_read_b128 v[8:11], v107 offset:96
	ds_read_b128 v[0:3], v107 offset:112
	s_waitcnt lgkmcnt(11)
	v_fma_f32 v12, -v93, v113, v12
	v_fma_f32 v4, v93, v112, v4
	v_fma_f32 v12, v92, v112, v12
	v_fma_f32 v4, v92, v113, v4
	v_fma_f32 v13, -v93, v4, v13
	v_fma_f32 v5, v93, v12, v5
	v_cvt_pk_bf16_f32 v112, v12, v4
	v_fma_f32 v113, v92, v12, v13
	v_fma_f32 v138, v92, v4, v5
	v_fma_f32 v4, -v93, v138, v14
	v_fma_f32 v5, v93, v113, v6
	v_fma_f32 v139, v92, v113, v4
	v_fma_f32 v140, v92, v138, v5
	v_cvt_pk_bf16_f32 v113, v113, v138
	v_add_u32_e32 v138, 0x4800, v108
	v_fma_f32 v141, -v93, v140, v15
	v_fma_f32 v142, v93, v139, v7
	ds_read_b128 v[12:15], v107 offset:9312
	ds_read_b128 v[4:7], v107 offset:9328
	ds_write2_b32 v138, v112, v113 offset1:68
	v_cvt_pk_bf16_f32 v112, v139, v140
	v_fma_f32 v113, v92, v139, v141
	v_fma_f32 v139, v92, v140, v142
	v_cvt_pk_bf16_f32 v140, v113, v139
	ds_write2_b32 v138, v112, v140 offset0:136 offset1:204
	s_waitcnt lgkmcnt(14)
	v_fma_f32 v112, -v93, v139, v118
	v_fma_f32 v114, v93, v113, v114
	v_fma_f32 v112, v92, v113, v112
	v_fma_f32 v113, v92, v139, v114
	v_fma_f32 v118, -v93, v113, v119
	v_fma_f32 v115, v93, v112, v115
	v_cvt_pk_bf16_f32 v114, v112, v113
	v_fma_f32 v112, v92, v112, v118
	v_fma_f32 v113, v92, v113, v115
	v_add_u32_e32 v118, 0x4c00, v108
	v_cvt_pk_bf16_f32 v115, v112, v113
	ds_write2_b32 v118, v114, v115 offset0:16 offset1:84
	v_fma_f32 v115, v93, v112, v116
	v_fma_f32 v114, -v93, v113, v120
	v_fma_f32 v112, v92, v112, v114
	v_fma_f32 v113, v92, v113, v115
	v_fma_f32 v115, -v93, v113, v121
	v_cvt_pk_bf16_f32 v114, v112, v113
	v_fma_f32 v116, v93, v112, v117
	v_fma_f32 v112, v92, v112, v115
	v_fma_f32 v113, v92, v113, v116
	v_cvt_pk_bf16_f32 v115, v112, v113
	ds_write2_b32 v118, v114, v115 offset0:152 offset1:220
	s_waitcnt lgkmcnt(13)
	v_fma_f32 v115, v93, v112, v130
	v_fma_f32 v114, -v93, v113, v122
	v_fma_f32 v112, v92, v112, v114
	v_fma_f32 v113, v92, v113, v115
	v_fma_f32 v115, -v93, v113, v123
	v_fma_f32 v116, v93, v112, v131
	v_cvt_pk_bf16_f32 v114, v112, v113
	v_fma_f32 v112, v92, v112, v115
	v_fma_f32 v113, v92, v113, v116
	v_add_u32_e32 v116, 0x5000, v108
	v_cvt_pk_bf16_f32 v115, v112, v113
	ds_write2_b32 v116, v114, v115 offset0:32 offset1:100
	v_fma_f32 v115, v93, v112, v132
	v_fma_f32 v114, -v93, v113, v124
	v_fma_f32 v112, v92, v112, v114
	v_fma_f32 v113, v92, v113, v115
	v_fma_f32 v115, -v93, v113, v125
	v_cvt_pk_bf16_f32 v114, v112, v113
	v_fma_f32 v117, v93, v112, v133
	v_fma_f32 v112, v92, v112, v115
	v_fma_f32 v113, v92, v113, v117
	v_cvt_pk_bf16_f32 v115, v112, v113
	ds_write2_b32 v116, v114, v115 offset0:168 offset1:236
	s_waitcnt lgkmcnt(14)
	v_fma_f32 v115, v93, v112, v134
	v_fma_f32 v114, -v93, v113, v126
	v_fma_f32 v112, v92, v112, v114
	v_fma_f32 v113, v92, v113, v115
	v_fma_f32 v115, -v93, v113, v127
	v_fma_f32 v116, v93, v112, v135
	v_cvt_pk_bf16_f32 v114, v112, v113
	v_fma_f32 v112, v92, v112, v115
	v_fma_f32 v113, v92, v113, v116
	v_add_u32_e32 v116, 0x5400, v108
	v_cvt_pk_bf16_f32 v115, v112, v113
	ds_write2_b32 v116, v114, v115 offset0:48 offset1:116
	v_fma_f32 v114, -v93, v113, v128
	v_fma_f32 v115, v93, v112, v136
	v_fma_f32 v112, v92, v112, v114
	v_fma_f32 v113, v92, v113, v115
	v_cvt_pk_bf16_f32 v114, v112, v113
	v_fma_f32 v115, -v93, v113, v129
	v_fma_f32 v117, v93, v112, v137
	v_fma_f32 v112, v92, v112, v115
	v_fma_f32 v113, v92, v113, v117
	s_waitcnt lgkmcnt(14)
	v_fma_f32 v28, -v93, v113, v28
	s_waitcnt lgkmcnt(12)
	v_fma_f32 v24, v93, v112, v24
	v_cvt_pk_bf16_f32 v115, v112, v113
	v_fma_f32 v28, v92, v112, v28
	v_fma_f32 v24, v92, v113, v24
	ds_write2_b32 v116, v114, v115 offset0:184 offset1:252
	v_fma_f32 v29, -v93, v24, v29
	v_fma_f32 v25, v93, v28, v25
	v_cvt_pk_bf16_f32 v112, v28, v24
	v_fma_f32 v28, v92, v28, v29
	v_fma_f32 v24, v92, v24, v25
	v_add_u32_e32 v29, 0x5800, v108
	v_cvt_pk_bf16_f32 v25, v28, v24
	ds_write2_b32 v29, v112, v25 offset0:64 offset1:132
	v_fma_f32 v25, -v93, v24, v30
	v_fma_f32 v26, v93, v28, v26
	v_fma_f32 v25, v92, v28, v25
	v_fma_f32 v24, v92, v24, v26
	v_cvt_pk_bf16_f32 v26, v25, v24
	v_fma_f32 v28, -v93, v24, v31
	v_fma_f32 v27, v93, v25, v27
	v_fma_f32 v25, v92, v25, v28
	v_fma_f32 v24, v92, v24, v27
	v_add_u32_e32 v28, 0x5a00, v108
	v_fma_f32 v20, -v93, v24, v20
	s_waitcnt lgkmcnt(13)
	v_fma_f32 v16, v93, v25, v16
	v_cvt_pk_bf16_f32 v27, v25, v24
	v_fma_f32 v20, v92, v25, v20
	v_fma_f32 v16, v92, v24, v16
	ds_write2_b32 v28, v26, v27 offset0:72 offset1:140
	v_fma_f32 v21, -v93, v16, v21
	v_fma_f32 v17, v93, v20, v17
	v_cvt_pk_bf16_f32 v24, v20, v16
	v_fma_f32 v20, v92, v20, v21
	v_fma_f32 v16, v92, v16, v17
	v_add_u32_e32 v21, 0x5c00, v108
	v_cvt_pk_bf16_f32 v17, v20, v16
	ds_write2_b32 v21, v24, v17 offset0:80 offset1:148
	v_fma_f32 v17, -v93, v16, v22
	v_fma_f32 v18, v93, v20, v18
	v_fma_f32 v17, v92, v20, v17
	v_fma_f32 v16, v92, v16, v18
	v_cvt_pk_bf16_f32 v18, v17, v16
	v_fma_f32 v20, -v93, v16, v23
	v_fma_f32 v19, v93, v17, v19
	v_fma_f32 v17, v92, v17, v20
	v_fma_f32 v16, v92, v16, v19
	v_add_u32_e32 v20, 0x5e00, v108
	s_waitcnt lgkmcnt(14)
	v_fma_f32 v8, -v93, v16, v8
	s_waitcnt lgkmcnt(12)
	v_fma_f32 v12, v93, v17, v12
	v_cvt_pk_bf16_f32 v19, v17, v16
	v_fma_f32 v8, v92, v17, v8
	v_fma_f32 v12, v92, v16, v12
	ds_write2_b32 v20, v18, v19 offset0:88 offset1:156
	v_fma_f32 v9, -v93, v12, v9
	v_fma_f32 v13, v93, v8, v13
	v_cvt_pk_bf16_f32 v16, v8, v12
	v_fma_f32 v8, v92, v8, v9
	v_fma_f32 v9, v92, v12, v13
	v_add_u32_e32 v13, 0x6000, v108
	v_cvt_pk_bf16_f32 v12, v8, v9
	ds_write2_b32 v13, v16, v12 offset0:96 offset1:164
	v_fma_f32 v10, -v93, v9, v10
	v_fma_f32 v12, v93, v8, v14
	v_fma_f32 v8, v92, v8, v10
	v_fma_f32 v9, v92, v9, v12
	v_cvt_pk_bf16_f32 v10, v8, v9
	v_fma_f32 v11, -v93, v9, v11
	v_fma_f32 v12, v93, v8, v15
	v_fma_f32 v8, v92, v8, v11
	v_fma_f32 v9, v92, v9, v12
	v_add_u32_e32 v12, 0x6200, v108
	v_fma_f32 v0, -v93, v9, v0
	s_waitcnt lgkmcnt(13)
	v_fma_f32 v4, v93, v8, v4
	v_cvt_pk_bf16_f32 v11, v8, v9
	v_fma_f32 v0, v92, v8, v0
	v_fma_f32 v4, v92, v9, v4
	ds_write2_b32 v12, v10, v11 offset0:104 offset1:172
	v_fma_f32 v1, -v93, v4, v1
	v_fma_f32 v5, v93, v0, v5
	v_cvt_pk_bf16_f32 v8, v0, v4
	v_fma_f32 v0, v92, v0, v1
	v_fma_f32 v1, v92, v4, v5
	v_add_u32_e32 v5, 0x6400, v108
	v_cvt_pk_bf16_f32 v4, v0, v1
	ds_write2_b32 v5, v8, v4 offset0:112 offset1:180
	v_fma_f32 v2, -v93, v1, v2
	v_fma_f32 v4, v93, v0, v6
	v_fma_f32 v0, v92, v0, v2
	v_fma_f32 v1, v92, v1, v4
	v_cvt_pk_bf16_f32 v2, v0, v1
	v_fma_f32 v3, -v93, v1, v3
	v_fma_f32 v4, v93, v0, v7
	v_fma_f32 v112, v92, v0, v3
	v_fma_f32 v113, v92, v1, v4
	v_add_u32_e32 v1, 0x6600, v108
	v_cvt_pk_bf16_f32 v0, v112, v113
	ds_write2_b32 v1, v2, v0 offset0:120 offset1:188
	ds_read_b128 v[0:3], v103 offset:18432
	ds_read_b128 v[4:7], v103 offset:18496
	ds_read_b128 v[8:11], v103 offset:22784
	ds_read_b128 v[12:15], v103 offset:22848
	s_waitcnt lgkmcnt(3)
	v_mfma_f32_16x16x32_bf16 v[0:3], v[0:3], v[48:51], 0
	s_waitcnt lgkmcnt(1)
	v_mfma_f32_16x16x32_bf16 v[8:11], v[8:11], v[48:51], 0
	v_mfma_f32_16x16x32_bf16 v[0:3], v[4:7], v[52:55], v[0:3]
	s_waitcnt lgkmcnt(0)
	v_mfma_f32_16x16x32_bf16 v[4:7], v[12:15], v[52:55], v[8:11]
	s_nop 4
	ds_read_b128 v[8:11], v103 offset:18560
	ds_read_b128 v[12:15], v103 offset:18624
	s_waitcnt lgkmcnt(1)
	v_mfma_f32_16x16x32_bf16 v[0:3], v[8:11], v[56:59], v[0:3]
	ds_read_b128 v[8:11], v103 offset:22912
	ds_read_b128 v[16:19], v103 offset:22976
	s_waitcnt lgkmcnt(1)
	v_mfma_f32_16x16x32_bf16 v[4:7], v[8:11], v[56:59], v[4:7]
	v_add_u32_e32 v10, 0x6800, v109
	ds_read2_b32 v[8:9], v10 offset0:128 offset1:144
	v_mfma_f32_16x16x32_bf16 v[0:3], v[12:15], v[60:63], v[0:3]
	s_waitcnt lgkmcnt(1)
	v_mfma_f32_16x16x32_bf16 v[4:7], v[16:19], v[60:63], v[4:7]
	s_waitcnt lgkmcnt(0)
	s_nop 4
	v_pk_fma_f32 v[0:1], v[90:91], v[8:9], v[0:1]
	s_nop 0
	v_mul_f32_e32 v8, 0x3d372713, v0
	v_mul_f32_e32 v8, v0, v8
	v_fma_f32 v8, v0, v8, v0
	v_mul_f32_e32 v8, 0x3f4c422a, v8
	v_mul_f32_e32 v8, 0xc038aa3b, v8
	v_exp_f32_e32 v11, v8
	v_mul_f32_e32 v8, 0x3d372713, v1
	v_mul_f32_e32 v8, v1, v8
	v_fma_f32 v8, v1, v8, v1
	v_mul_f32_e32 v8, 0x3f4c422a, v8
	v_mul_f32_e32 v8, 0xc038aa3b, v8
	v_exp_f32_e32 v12, v8
	ds_read2_b32 v[8:9], v10 offset0:160 offset1:176
	v_add_f32_e32 v10, 1.0, v11
	v_rcp_f32_e32 v10, v10
	v_add_f32_e32 v11, 1.0, v12
	v_rcp_f32_e32 v11, v11
	s_waitcnt lgkmcnt(0)
	v_pk_fma_f32 v[2:3], v[90:91], v[8:9], v[2:3]
	v_add_u32_e32 v12, 0x6c00, v109
	v_mul_f32_e32 v8, 0x3d372713, v2
	v_mul_f32_e32 v9, 0x3d372713, v3
	v_mul_f32_e32 v8, v2, v8
	v_mul_f32_e32 v9, v3, v9
	v_fma_f32 v8, v2, v8, v2
	v_fma_f32 v9, v3, v9, v3
	v_mul_f32_e32 v8, 0x3f4c422a, v8
	v_mul_f32_e32 v9, 0x3f4c422a, v9
	v_mul_f32_e32 v8, 0xc038aa3b, v8
	v_mul_f32_e32 v9, 0xc038aa3b, v9
	v_exp_f32_e32 v8, v8
	v_exp_f32_e32 v9, v9
	v_pk_mul_f32 v[0:1], v[0:1], v[10:11]
	ds_read2_b32 v[10:11], v12 offset0:128 offset1:144
	v_add_f32_e32 v8, 1.0, v8
	v_add_f32_e32 v9, 1.0, v9
	v_rcp_f32_e32 v8, v8
	v_rcp_f32_e32 v9, v9
	s_nop 0
	v_pk_mul_f32 v[2:3], v[2:3], v[8:9]
	v_cvt_pk_bf16_f32 v8, v0, v1
	s_waitcnt lgkmcnt(0)
	v_pk_fma_f32 v[0:1], v[90:91], v[10:11], v[4:5]
	v_cvt_pk_bf16_f32 v9, v2, v3
	v_mul_f32_e32 v2, 0x3d372713, v0
	v_mul_f32_e32 v2, v0, v2
	v_fma_f32 v2, v0, v2, v0
	v_mul_f32_e32 v2, 0x3f4c422a, v2
	v_mul_f32_e32 v2, 0xc038aa3b, v2
	v_exp_f32_e32 v4, v2
	v_mul_f32_e32 v2, 0x3d372713, v1
	v_mul_f32_e32 v2, v1, v2
	v_fma_f32 v2, v1, v2, v1
	v_mul_f32_e32 v2, 0x3f4c422a, v2
	v_mul_f32_e32 v2, 0xc038aa3b, v2
	v_exp_f32_e32 v5, v2
	ds_read2_b32 v[2:3], v12 offset0:160 offset1:176
	v_add_f32_e32 v4, 1.0, v4
	v_rcp_f32_e32 v4, v4
	v_add_f32_e32 v5, 1.0, v5
	v_rcp_f32_e32 v5, v5
	s_waitcnt lgkmcnt(0)
	v_pk_fma_f32 v[2:3], v[90:91], v[2:3], v[6:7]
	ds_write_b16 v110, v8 offset:29184
	v_mul_f32_e32 v6, 0x3d372713, v2
	v_mul_f32_e32 v7, 0x3d372713, v3
	v_mul_f32_e32 v6, v2, v6
	v_mul_f32_e32 v7, v3, v7
	v_fma_f32 v6, v2, v6, v2
	v_fma_f32 v7, v3, v7, v3
	v_mul_f32_e32 v6, 0x3f4c422a, v6
	v_mul_f32_e32 v7, 0x3f4c422a, v7
	v_mul_f32_e32 v6, 0xc038aa3b, v6
	v_mul_f32_e32 v7, 0xc038aa3b, v7
	v_exp_f32_e32 v6, v6
	v_exp_f32_e32 v7, v7
	v_pk_mul_f32 v[0:1], v[0:1], v[4:5]
	ds_write_b16_d16_hi v110, v8 offset:29216
	v_add_f32_e32 v6, 1.0, v6
	v_add_f32_e32 v7, 1.0, v7
	v_rcp_f32_e32 v6, v6
	v_rcp_f32_e32 v7, v7
	v_cvt_pk_bf16_f32 v0, v0, v1
	ds_write_b16 v110, v9 offset:29248
	ds_write_b16_d16_hi v110, v9 offset:29280
	v_lshl_add_u64 v[4:5], v[96:97], 0, s[36:37]
	v_pk_mul_f32 v[2:3], v[2:3], v[6:7]
	s_add_u32 s36, s36, 0x10000
	v_cvt_pk_bf16_f32 v1, v2, v3
	ds_write_b16 v110, v0 offset:29696
	ds_write_b16_d16_hi v110, v0 offset:29728
	ds_write_b16 v110, v1 offset:29760
	ds_write_b16_d16_hi v110, v1 offset:29792
	ds_read_b128 v[0:3], v104 offset:29184
	s_waitcnt vmcnt(0)
	v_pk_add_f32 v[228:229], v[228:229], v[232:233]
	v_pk_add_f32 v[226:227], v[226:227], v[230:231]
	v_pk_add_f32 v[228:229], v[228:229], v[238:239]
	v_pk_add_f32 v[226:227], v[226:227], v[236:237]
	v_pk_add_f32 v[228:229], v[228:229], v[242:243]
	v_pk_add_f32 v[226:227], v[226:227], v[240:241]
	s_nop 0
	v_pk_mov_b32 v[230:231], v[226:227], v[228:229] op_sel:[1,0]
	v_mov_b32_e32 v227, v229
	v_pk_add_f32 v[226:227], v[230:231], v[226:227]
	s_nop 0
	v_add_f32_e32 v230, v226, v227
	v_fmamk_f32 v230, v230, 0x3a800000, v245
	v_rsq_f32_e32 v111, v230
	s_addc_u32 s37, s37, 0
	s_cmp_eq_u32 s36, 0x400000
	s_waitcnt lgkmcnt(0)
	global_store_dwordx4 v[4:5], v[0:3], off
	s_nop 1
	v_mov_b64_e32 v[0:1], v[72:73]
	v_mov_b64_e32 v[2:3], v[74:75]
	v_mov_b32_e32 v4, v111
	s_cbranch_scc1 .LBB0_322
